# attention unit prologue: tile-1 K/V staged by LDS-DMA issued at unit start instead of VGPR loads + ds_write mid QK(0)
# speedup vs baseline: 1.0045x; 1.0045x over previous
; DI int v_st(int k, int c) { const int kk = (k & ~0xC) | ((k & 4) << 1) | ((k & 8) >> 1); return ((kk >> 3) * 4 + (c >> 5)) * 512 + ((kk & 7) * 32 + (c & 31)) * 2; }
; DI int v_rd_base(int lane) { return ((lane & 3) << 3) | (((lane >> 2) & 3) << 6) | (((lane >> 4) & 1) << 5) | (((lane >> 5) & 1) << 8); }
; #define SLOAD(i, k0) do { sr_[i].vs0 = *(const bf16x8*)(&Vh[(long)((k0) + sr) * LDA_ + sc]); sr_[i].vs1 = *(const bf16x8*)(&Vh[(long)((k0) + 32 + sr) * LDA_ + sc]); \
;     sr_[i].ks0 = *(const bf16x8*)(&Kh[(long)((k0) + sr) * LDA_ + sc]); sr_[i].ks1 = *(const bf16x8*)(&Kh[(long)((k0) + 32 + sr) * LDA_ + sc]); } while (0)
; #define SWAIT() asm volatile("s_waitcnt vmcnt(0)" ::: "memory")
; DI void attn_unit(const bf16_t* __restrict__ Qb, const bf16_t* __restrict__ Kh, const bf16_t* __restrict__ Vh, bf16_t* __restrict__ Ob, const float* __restrict__ onw, int seq, char* lds) {
;     int tid_ = threadIdx.x; asm volatile("" : "+v"(tid_));
;     const int tid = tid_, wid = tid >> 6, lane = tid & 63, r32 = lane & 31, hi = lane >> 5;
;     char* V_lds = lds; char* K_lds = lds + 2 * SHM_V;
;     float* wsf = (float*)(lds + 2 * SHM_V + 2 * SHM_K) + wid * 64; float* li_l = wsf; float* al_l = wsf + 32;
;     float m_reg = 0.f, l_reg = 0; f32x16 o[4]; bf16x8 qr[8];
; #pragma unroll
;     for (int d = 0; d < 4; ++d)
; #pragma unroll
;         for (int i = 0; i < 16; ++i) o[d][i] = 0.f;
;     const bf16_t* Qw = Qb + (long)((wid & 3) * 32 + r32) * LDA_ + (wid >> 2) * 128 + hi * 8;
; #pragma unroll
;     for (int d0 = 0; d0 < 8; ++d0) qr[d0] = *(const bf16x8*)(Qw + d0 * 16);
;     const int sr = tid >> 4, sc = (tid & 15) * 8, vst0 = v_st(sr, sc), vst1 = v_st(32 + sr, sc);
;     const int vb0 = (int)(uintptr_t)V_lds + v_rd_base(lane);
;     struct { bf16x8 vs0, vs1, ks0, ks1; } sr_[1];
;     ...
;     f32x16 pA0, pA1, pB0, pB1; float alA, alB; bf16x8 pa0, pa1, pa2, pa3; const int NT = seq / 64;
;     constexpr int SE = 0, SO = 0;
;     SLOAD(SE, 0); asm volatile("s_waitcnt vmcnt(0)" ::: "memory"); SWRITE(0, SE); __syncthreads();
;     qkt(pA0, pA1, K_lds, qr, 0.f, r32, hi); partialSM<true>(pA0, pA1, m_reg, alA);
;     SLOAD(SO, 64);
;     SWAIT(); SWRITE(1, SO); __syncthreads();
.LBB0_579:
	s_and_b32 s12, s14, 1
	s_lshl_b32 s2, s15, 7
	s_add_u32 s2, s68, s2
	s_addc_u32 s3, s69, 0
	s_lshl_b64 s[66:67], s[2:3], 10
	s_lshl_b64 s[2:3], s[2:3], 11
	s_add_u32 s2, s30, s2
	s_addc_u32 s3, s31, s3
	s_lshl_b32 s72, s12, 8
	s_lshl_b32 s12, s12, 9
	s_add_u32 s2, s2, s12
	s_waitcnt vmcnt(0)
	v_mov_b32_e32 v80, v192
	s_addc_u32 s3, s3, 0
	s_lshl_b64 s[14:15], s[68:69], 11
	s_add_u32 s12, s30, s14
	v_ashrrev_i32_e32 v48, 4, v80
	v_lshlrev_b32_e32 v20, 3, v80
	v_add_u32_e32 v16, 32, v48
	s_addc_u32 s15, s31, s15
	v_and_b32_e32 v0, 0x78, v20
	v_ashrrev_i32_e32 v49, 31, v48
	v_ashrrev_i32_e32 v17, 31, v16
	s_add_u32 s14, s12, s72
	v_lshlrev_b32_e32 v21, 1, v0
	v_lshlrev_b64 v[0:1], 11, v[48:49]
	v_lshlrev_b64 v[4:5], 11, v[16:17]
	s_addc_u32 s15, s15, 0
	v_or_b32_e32 v0, v0, v21
	v_or_b32_e32 v4, v4, v21
	v_lshl_add_u64 v[50:51], s[14:15], 0, v[0:1]
	v_lshl_add_u64 v[12:13], s[14:15], 0, v[4:5]
	s_add_u32 s98, s14, 0x20400
	s_addc_u32 s99, s15, 0
	v_readfirstlane_b32 s100, v80
	v_and_b32_e32 v250, 63, v80
	v_lshrrev_b32_e32 v251, 6, v80
	v_lshrrev_b32_e32 v252, 4, v250
	v_and_b32_e32 v253, 1, v251
	v_lshl_add_u32 v253, v253, 2, v252
	v_and_b32_e32 v246, 15, v250
	v_xor_b32_e32 v246, v246, v253
	v_lshlrev_b32_e32 v246, 4, v246
	v_lshl_add_u32 v252, v251, 2, v252
	v_lshl_add_u32 v246, v252, 11, v246
	v_add_u32_e32 v246, 0x20000, v246
	v_add_u32_e32 v247, 0x10000, v246
	v_bfe_u32 v252, v250, 2, 3
	v_and_b32_e32 v253, 3, v252
	v_lshrrev_b32_e32 v252, 2, v252
	v_lshl_add_u32 v253, v252, 3, v253
	v_bfe_u32 v252, v251, 1, 1
	v_lshl_add_u32 v253, v252, 2, v253
	v_bfe_u32 v252, v251, 2, 1
	v_lshl_add_u32 v253, v252, 4, v253
	v_lshlrev_b32_e32 v248, 11, v253
	v_and_b32_e32 v252, 1, v251
	v_lshlrev_b32_e32 v252, 1, v252
	v_lshrrev_b32_e32 v253, 5, v250
	v_add_u32_e32 v252, v252, v253
	v_and_b32_e32 v253, 3, v250
	v_lshl_add_u32 v252, v252, 2, v253
	v_lshl_add_u32 v248, v252, 4, v248
	v_add_u32_e32 v248, 0x200, v248
	v_add_u32_e32 v249, 0x10000, v248
	s_lshl_b32 s100, s100, 4
	s_add_u32 m0, s100, 0x4000
	s_nop 0
	global_load_lds_dwordx4 v248, s[98:99]
	s_add_u32 m0, s100, 0x6000
	s_nop 0
	global_load_lds_dwordx4 v249, s[98:99]
	s_sub_u32 s98, s98, 0x20000
	s_subb_u32 s99, s99, 0
	s_add_u32 m0, s100, 0xc000
	s_nop 0
	global_load_lds_dwordx4 v246, s[98:99]
	s_add_u32 m0, s100, 0xe000
	s_nop 0
	global_load_lds_dwordx4 v247, s[98:99]
	s_add_u32 s98, s98, 0x20000
	s_addc_u32 s99, s99, 0
	global_load_dwordx4 v[0:3], v[50:51], off offset:1536
	global_load_dwordx4 v[4:7], v[12:13], off offset:1536
	global_load_dwordx4 v[8:11], v[50:51], off offset:1024
	s_nop 0
	global_load_dwordx4 v[12:15], v[12:13], off offset:1024
	v_lshrrev_b32_e32 v17, 1, v80
	v_and_b32_e32 v155, 31, v80
	v_and_b32_e32 v170, 0x60, v17
	v_or_b32_e32 v17, v170, v155
	v_lshlrev_b32_e32 v184, 11, v17
	v_ashrrev_i32_e32 v17, 1, v80
	v_and_b32_e32 v148, 0xffffff80, v17
	v_bfe_u32 v151, v80, 5, 1
	v_lshl_add_u64 v[18:19], s[2:3], 0, v[184:185]
	v_ashrrev_i32_e32 v149, 31, v148
	v_lshl_add_u64 v[18:19], v[148:149], 1, v[18:19]
	v_lshlrev_b32_e32 v184, 4, v151
	v_lshl_add_u64 v[18:19], v[18:19], 0, v[184:185]
	global_load_dwordx4 v[140:143], v[18:19], off
	global_load_dwordx4 v[136:139], v[18:19], off offset:32
	global_load_dwordx4 v[132:135], v[18:19], off offset:64
	global_load_dwordx4 v[128:131], v[18:19], off offset:96
	global_load_dwordx4 v[124:127], v[18:19], off offset:128
	global_load_dwordx4 v[120:123], v[18:19], off offset:160
	global_load_dwordx4 v[116:119], v[18:19], off offset:192
	global_load_dwordx4 v[112:115], v[18:19], off offset:224
	v_and_b32_e32 v22, 0xfffff0, v48
	v_lshlrev_b32_e32 v23, 1, v48
	v_lshrrev_b32_e32 v24, 1, v48
	v_and_b32_e32 v25, 3, v48
	v_and_or_b32 v22, v23, 8, v22
	v_and_or_b32 v23, v24, 4, v25
	v_and_b32_e32 v24, 0xfffff0, v16
	v_lshlrev_b32_e32 v25, 1, v16
	v_and_b32_e32 v17, 0x70, v80
	v_bfe_u32 v20, v20, 5, 2
	v_lshlrev_b32_e32 v26, 8, v48
	v_lshlrev_b32_e32 v16, 8, v16
	v_lshrrev_b32_e32 v22, 1, v22
	v_and_or_b32 v24, v25, 8, v24
	v_and_b32_e32 v27, 48, v21
	v_bitop3_b32 v25, v21, v26, v17 bitop3:0xde
	v_bitop3_b32 v16, v21, v16, v17 bitop3:0xde
	v_or_b32_e32 v17, v22, v20
	v_lshrrev_b32_e32 v21, 1, v24
	v_lshlrev_b32_e32 v23, 6, v23
	v_add_u32_e32 v205, 0, v16
	v_lshlrev_b32_e32 v16, 9, v17
	v_or_b32_e32 v17, v21, v20
	v_or3_b32 v16, v16, v23, v27
	v_lshlrev_b32_e32 v17, 9, v17
	v_lshlrev_b32_e32 v66, 4, v80
	v_or3_b32 v17, v17, v23, v27
	v_add_u32_e32 v206, 0, v16
	v_add_u32_e32 v204, 0, v25
	v_add_u32_e32 v207, 0, v17
	s_waitcnt vmcnt(0)
	s_mov_b64 s[2:3], 0x20000
	v_and_b32_e32 v81, 63, v80
	s_mov_b32 s12, s13
	s_mov_b32 s14, s13
	s_mov_b32 s15, s13
	s_mov_b32 s16, s13
	s_mov_b32 s17, s13
	s_mov_b32 s18, s13
	s_mov_b32 s19, s13
	s_mov_b32 s20, s13
	s_mov_b32 s21, s13
	s_mov_b32 s22, s13
	s_waitcnt vmcnt(11)
	ds_write_b128 v206, v[0:3]
	s_waitcnt vmcnt(10)
	ds_write_b128 v207, v[4:7]
	s_waitcnt vmcnt(9)
	ds_write_b128 v204, v[8:11] offset:32768
	s_waitcnt vmcnt(8)
	ds_write_b128 v205, v[12:15] offset:32768
	v_lshlrev_b32_e32 v12, 8, v155
	v_and_b32_e32 v13, 0x70, v66
	v_bitop3_b32 v0, v184, v12, v13 bitop3:0xde
	v_add_u32_e32 v183, 0, v0
	s_waitcnt lgkmcnt(0)
	s_barrier
; #define MFMA32(a, b, c) __builtin_amdgcn_mfma_f32_32x32x16_bf16((a), (b), (c), 0, 0, 0)
; #define SLOAD(i, k0) do { sr_[i].vs0 = *(const bf16x8*)(&Vh[(long)((k0) + sr) * LDA_ + sc]); sr_[i].vs1 = *(const bf16x8*)(&Vh[(long)((k0) + 32 + sr) * LDA_ + sc]); \
;     sr_[i].ks0 = *(const bf16x8*)(&Kh[(long)((k0) + sr) * LDA_ + sc]); sr_[i].ks1 = *(const bf16x8*)(&Kh[(long)((k0) + 32 + sr) * LDA_ + sc]); } while (0)
; #define SWRITE(b, i) do { *(bf16x8*)(V_lds + (b) * SHM_V + vst0) = sr_[i].vs0;          \
;     *(bf16x8*)(V_lds + (b) * SHM_V + vst1) = sr_[i].vs1; int kc = sc * 2;               \
;     *(bf16x8*)(K_lds + (b) * SHM_K + KSWZ(sr, kc)) = sr_[i].ks0;                       \
;     *(bf16x8*)(K_lds + (b) * SHM_K + KSWZ(32 + sr, kc)) = sr_[i].ks1; } while (0)
; #define SWAIT() asm volatile("s_waitcnt vmcnt(0)" ::: "memory")
; DI void qkt(f32x16& p0, f32x16& p1, const char* Ks, const bf16x8* qr, float negm, int r32, int hi) {
; #pragma unroll
;     for (int i = 0; i < 16; ++i) { p0[i] = negm; p1[i] = negm; }
; #pragma unroll
;     for (int d0 = 0; d0 < 8; ++d0) { const int cb = (d0 * 16 + hi * 8) * 2;
;         bf16x8 b0 = *(const bf16x8*)(Ks + KSWZ(r32, cb));
;         bf16x8 b1 = *(const bf16x8*)(Ks + KSWZ(32 + r32, cb));
;         p0 = MFMA32(b0, qr[d0], p0);
;         p1 = MFMA32(b1, qr[d0], p1); }
; }
; DI void attn_unit(const bf16_t* __restrict__ Qb, const bf16_t* __restrict__ Kh, const bf16_t* __restrict__ Vh, bf16_t* __restrict__ Ob, const float* __restrict__ onw, int seq, char* lds) {
;     ...
;     SLOAD(SE, 0); asm volatile("s_waitcnt vmcnt(0)" ::: "memory"); SWRITE(0, SE); __syncthreads();
;     qkt(pA0, pA1, K_lds, qr, 0.f, r32, hi); partialSM<true>(pA0, pA1, m_reg, alA);
;     SLOAD(SO, 64);
;     SWAIT(); SWRITE(1, SO); __syncthreads();
	ds_read_b128 v[0:3], v183 offset:32768
	ds_read_b128 v[4:7], v183 offset:40960
	s_waitcnt vmcnt(7) lgkmcnt(1)
	v_mfma_f32_32x32x16_bf16 v[32:47], v[0:3], v[140:143], 0
	v_or_b32_e32 v0, 32, v184
	v_bitop3_b32 v0, v0, v12, v13 bitop3:0xde
	v_add_u32_e32 v208, 0, v0
	v_lshl_add_u64 v[8:9], v[50:51], 0, s[2:3]
	v_lshl_add_u64 v[10:11], v[50:51], 0, s[56:57]
	s_add_i32 s2, 0, 0x10000
	s_cmp_lg_u32 0, -1
	s_waitcnt lgkmcnt(0)
	v_mfma_f32_32x32x16_bf16 v[16:31], v[4:7], v[140:143], 0
	ds_read_b128 v[0:3], v208 offset:32768
	ds_read_b128 v[4:7], v208 offset:40960
	s_mov_b32 s23, s13
	s_mov_b32 s24, s13
	s_mov_b32 s25, s13
	s_mov_b32 s26, s13
	s_mov_b32 s27, s13
	s_cselect_b32 s43, 0, 0
	s_waitcnt vmcnt(6) lgkmcnt(1)
	v_mfma_f32_32x32x16_bf16 v[32:47], v[0:3], v[136:139], v[32:47]
	v_or_b32_e32 v0, 64, v184
	v_bitop3_b32 v0, v0, v12, v13 bitop3:0xde
	v_add_u32_e32 v209, 0, v0
	s_mov_b32 s42, 2
	v_mov_b32_e32 v173, 0
	s_waitcnt lgkmcnt(0)
	v_mfma_f32_32x32x16_bf16 v[16:31], v[4:7], v[136:139], v[16:31]
	ds_read_b128 v[0:3], v209 offset:32768
	ds_read_b128 v[4:7], v209 offset:40960
	s_waitcnt vmcnt(5) lgkmcnt(1)
	v_mfma_f32_32x32x16_bf16 v[32:47], v[0:3], v[132:135], v[32:47]
	v_or_b32_e32 v0, 0x60, v184
	v_bitop3_b32 v0, v0, v12, v13 bitop3:0xde
	v_add_u32_e32 v210, 0, v0
	s_waitcnt lgkmcnt(0)
	v_mfma_f32_32x32x16_bf16 v[16:31], v[4:7], v[132:135], v[16:31]
	ds_read_b128 v[0:3], v210 offset:32768
	ds_read_b128 v[4:7], v210 offset:40960
	s_waitcnt vmcnt(4) lgkmcnt(1)
	v_mfma_f32_32x32x16_bf16 v[32:47], v[0:3], v[128:131], v[32:47]
	v_or_b32_e32 v0, 0x80, v184
	v_bitop3_b32 v0, v0, v12, v13 bitop3:0xde
	v_add_u32_e32 v211, 0, v0
	ds_read_b128 v[0:3], v211 offset:32768
	s_waitcnt lgkmcnt(1)
	v_mfma_f32_32x32x16_bf16 v[16:31], v[4:7], v[128:131], v[16:31]
	ds_read_b128 v[4:7], v211 offset:40960
	v_lshlrev_b32_e32 v8, 3, v81
	v_lshlrev_b32_e32 v10, 1, v80
	s_waitcnt vmcnt(7) lgkmcnt(1)
	v_mfma_f32_32x32x16_bf16 v[32:47], v[0:3], v[124:127], v[32:47]
	v_or_b32_e32 v0, 0xa0, v184
	v_bitop3_b32 v0, v0, v12, v13 bitop3:0xde
	v_add_u32_e32 v212, 0, v0
	ds_read_b128 v[0:3], v212 offset:32768
	s_waitcnt lgkmcnt(1)
	v_mfma_f32_32x32x16_bf16 v[16:31], v[4:7], v[124:127], v[16:31]
	v_and_b32_e32 v4, 0x3fffffc0, v80
	v_lshl_add_u32 v171, v4, 2, s2
	ds_read_b128 v[4:7], v212 offset:40960
	v_cmp_gt_u32_e64 s[2:3], 32, v81
	v_lshl_add_u32 v172, v155, 2, v171
	s_waitcnt vmcnt(6) lgkmcnt(1)
	v_mfma_f32_32x32x16_bf16 v[32:47], v[0:3], v[120:123], v[32:47]
	v_and_b32_e32 v0, 0xc0, v66
	v_and_or_b32 v9, v8, 24, v0
	v_or_b32_e32 v0, 0xc0, v184
	v_bitop3_b32 v0, v0, v12, v13 bitop3:0xde
	v_add_u32_e32 v213, 0, v0
	ds_read_b128 v[0:3], v213 offset:32768
	s_waitcnt lgkmcnt(1)
	v_mfma_f32_32x32x16_bf16 v[16:31], v[4:7], v[120:123], v[16:31]
	v_and_b32_e32 v4, 32, v10
	v_and_b32_e32 v5, 0x100, v8
	v_or3_b32 v82, v9, v4, v5
	ds_read_b128 v[4:7], v213 offset:40960
	v_add_u32_e32 v175, s43, v82
	s_addk_i32 s43, 0x4000
	v_add_u32_e32 v174, s43, v82
	s_waitcnt vmcnt(5) lgkmcnt(1)
	v_mfma_f32_32x32x16_bf16 v[32:47], v[0:3], v[116:119], v[32:47]
	v_or_b32_e32 v0, 0xe0, v184
	v_bitop3_b32 v0, v0, v12, v13 bitop3:0xde
	v_add_u32_e32 v214, 0, v0
	ds_read_b128 v[0:3], v214 offset:32768
	ds_read_b128 v[66:69], v214 offset:40960
	s_waitcnt vmcnt(0)
	s_waitcnt vmcnt(3)
	s_waitcnt vmcnt(2)
	s_waitcnt vmcnt(1)
	s_waitcnt vmcnt(0)
	s_waitcnt lgkmcnt(6)
	v_mfma_f32_32x32x16_bf16 v[16:31], v[4:7], v[116:119], v[16:31]
	s_waitcnt lgkmcnt(0)
	s_barrier
	v_mfma_f32_32x32x16_bf16 v[32:47], v[0:3], v[112:115], v[32:47]
	v_mov_b64_e32 v[0:1], s[12:13]
	v_mov_b64_e32 v[14:15], s[26:27]
	v_mov_b64_e32 v[2:3], s[14:15]
	v_mov_b64_e32 v[4:5], s[16:17]
	v_mov_b64_e32 v[6:7], s[18:19]
	v_mov_b64_e32 v[8:9], s[20:21]
	v_mov_b64_e32 v[10:11], s[22:23]
	v_mfma_f32_32x32x16_bf16 v[16:31], v[66:69], v[112:115], v[16:31]
	s_nop 3
	v_max_f32_e32 v66, v33, v33
	v_max_f32_e32 v67, v32, v32
	v_max_f32_e32 v66, v67, v66
	v_max3_f32 v66, v66, v34, v35
	v_max3_f32 v66, v66, v36, v37
	v_max3_f32 v66, v66, v38, v39
	v_max3_f32 v66, v66, v40, v41
	v_max3_f32 v66, v66, v42, v43
	v_max3_f32 v66, v66, v44, v45
	v_max3_f32 v66, v66, v46, v47
	v_max3_f32 v66, v66, v16, v17
	v_max3_f32 v66, v66, v18, v19
	v_max3_f32 v66, v66, v20, v21
	v_max3_f32 v66, v66, v22, v23
	v_max3_f32 v66, v66, v24, v25
	v_max3_f32 v66, v66, v26, v27
	v_max3_f32 v66, v66, v28, v29
	v_max3_f32 v66, v66, v30, v31
	v_mov_b32_e32 v67, v66
	s_nop 1
	v_permlane32_swap_b32_e32 v66, v67
	v_max_f32_e32 v50, v67, v67
	v_max_f32_e32 v51, v66, v66
	v_max_f32_e32 v50, v51, v50
	v_exp_f32_e32 v32, v32
	v_exp_f32_e64 v150, -v50
	v_exp_f32_e32 v33, v33
	v_exp_f32_e32 v34, v34
	v_exp_f32_e32 v35, v35
	v_exp_f32_e32 v36, v36
	v_exp_f32_e32 v37, v37
	v_exp_f32_e32 v38, v38
	v_exp_f32_e32 v39, v39
	v_exp_f32_e32 v40, v40
	v_exp_f32_e32 v42, v42
	v_exp_f32_e32 v44, v44
	v_exp_f32_e32 v46, v46
	v_exp_f32_e32 v47, v47
	v_exp_f32_e32 v45, v45
	v_exp_f32_e32 v43, v43
	v_exp_f32_e32 v41, v41
	v_sub_f32_e32 v66, v18, v50
	v_sub_f32_e32 v65, v17, v50
	v_sub_f32_e32 v64, v16, v50
	v_lshl_add_u64 v[16:17], s[68:69], 0, v[48:49]
	v_and_b32_e32 v18, 15, v80
	v_lshlrev_b64 v[16:17], 11, v[16:17]
	v_lshlrev_b32_e32 v18, 4, v18
	v_or3_b32 v16, v16, s72, v18
	v_mov_b64_e32 v[12:13], s[24:25]
	v_pk_mul_f32 v[146:147], v[46:47], v[150:151] op_sel_hi:[1,0]
	v_pk_mul_f32 v[160:161], v[44:45], v[150:151] op_sel_hi:[1,0]
	v_pk_mul_f32 v[164:165], v[42:43], v[150:151] op_sel_hi:[1,0]
	v_pk_mul_f32 v[168:169], v[40:41], v[150:151] op_sel_hi:[1,0]
	v_pk_mul_f32 v[156:157], v[38:39], v[150:151] op_sel_hi:[1,0]
	v_pk_mul_f32 v[158:159], v[36:37], v[150:151] op_sel_hi:[1,0]
	v_pk_mul_f32 v[162:163], v[34:35], v[150:151] op_sel_hi:[1,0]
	v_pk_mul_f32 v[166:167], v[32:33], v[150:151] op_sel_hi:[1,0]
	v_sub_f32_e32 v79, v31, v50
	v_sub_f32_e32 v78, v30, v50
	v_sub_f32_e32 v77, v29, v50
	v_sub_f32_e32 v76, v28, v50
	v_sub_f32_e32 v75, v27, v50
	v_sub_f32_e32 v74, v26, v50
	v_sub_f32_e32 v73, v25, v50
	v_sub_f32_e32 v72, v24, v50
	v_sub_f32_e32 v71, v23, v50
	v_sub_f32_e32 v70, v22, v50
	v_sub_f32_e32 v69, v21, v50
	v_sub_f32_e32 v68, v20, v50
	v_sub_f32_e32 v67, v19, v50
	v_add_f32_e32 v215, 0, v50
	v_lshl_add_u64 v[152:153], s[40:41], 0, v[16:17]
	v_mov_b64_e32 v[62:63], v[14:15]
	v_mov_b64_e32 v[30:31], v[14:15]
	v_mov_b64_e32 v[46:47], v[14:15]
	v_mov_b64_e32 v[60:61], v[12:13]
	v_mov_b64_e32 v[58:59], v[10:11]
	v_mov_b64_e32 v[56:57], v[8:9]
	v_mov_b64_e32 v[54:55], v[6:7]
	v_mov_b64_e32 v[52:53], v[4:5]
	v_mov_b64_e32 v[50:51], v[2:3]
	v_mov_b64_e32 v[48:49], v[0:1]
	v_mov_b64_e32 v[28:29], v[12:13]
	v_mov_b64_e32 v[26:27], v[10:11]
	v_mov_b64_e32 v[24:25], v[8:9]
	v_mov_b64_e32 v[22:23], v[6:7]
	v_mov_b64_e32 v[20:21], v[4:5]
	v_mov_b64_e32 v[18:19], v[2:3]
	v_mov_b64_e32 v[16:17], v[0:1]
	v_mov_b64_e32 v[44:45], v[12:13]
	v_mov_b64_e32 v[42:43], v[10:11]
	v_mov_b64_e32 v[40:41], v[8:9]
	v_mov_b64_e32 v[38:39], v[6:7]
	v_mov_b64_e32 v[36:37], v[4:5]
	v_mov_b64_e32 v[34:35], v[2:3]
	v_mov_b64_e32 v[32:33], v[0:1]
